# adaLN GEMV loop rotated: 4-8 ada_w loads in flight at all times (was: 8 issued, drained to 0 every trip)
# baseline (speedup 1.0000x reference)
; __device__ __forceinline__ void phase_prep(const Params& P, LAS unsigned char* lds, int l, const XcdBarrier& bar) {
;     ...
;     for (int it = wg; it < NLAYER * (NMOD / 64); it += G) {
;         const int ll = it / (NMOD / 64), ch = it % (NMOD / 64), col0 = ch * 64;
;         const float* wp = P.ada_w + ((size_t)ll * DM + kg) * NMOD + col0 + 4 * cq;
;         f32x4 a0 = {0, 0, 0, 0}, a1 = a0, a2 = a0, a3 = a0;
; #pragma unroll 8
;         for (int kk = 0; kk < 64; ++kk) { const f32x4 wv = __builtin_nontemporal_load((const f32x4*)(wp + (size_t)kk * 32 * NMOD)); const int k = kg + 32 * kk;
;             a0 += wv * sc[k]; a1 += wv * sc[DM + k]; a2 += wv * sc[2 * DM + k]; a3 += wv * sc[3 * DM + k]; }
.LBB0_272:
	s_mov_b32 s9, 0x480000
	s_mov_b32 s19, 0x6c0000
	s_mov_b32 s24, 0x900000
	s_mov_b32 s25, 0xb40000
	s_mov_b32 s29, 0xd80000
	s_mov_b32 s30, 0xfc0000
	v_lshl_add_u64 v[218:219], v[38:39], 0, s[58:59]
	global_load_dwordx4 v[74:77], v[218:219], off nt
	v_add_co_u32_e32 v78, vcc, s2, v218
	s_nop 1
	v_addc_co_u32_e32 v79, vcc, 0, v219, vcc
	global_load_dwordx4 v[78:81], v[78:79], off nt
	v_add_co_u32_e32 v82, vcc, s9, v218
	s_nop 1
	v_addc_co_u32_e32 v83, vcc, 0, v219, vcc
	global_load_dwordx4 v[82:85], v[82:83], off nt
	v_add_co_u32_e32 v86, vcc, s19, v218
	s_nop 1
	v_addc_co_u32_e32 v87, vcc, 0, v219, vcc
	global_load_dwordx4 v[86:89], v[86:87], off nt
	v_add_co_u32_e32 v90, vcc, s24, v218
	s_nop 1
	v_addc_co_u32_e32 v91, vcc, 0, v219, vcc
	global_load_dwordx4 v[90:93], v[90:91], off nt
	v_add_co_u32_e32 v94, vcc, s25, v218
	s_nop 1
	v_addc_co_u32_e32 v95, vcc, 0, v219, vcc
	global_load_dwordx4 v[94:97], v[94:95], off nt
	v_add_co_u32_e32 v98, vcc, s29, v218
	s_nop 1
	v_addc_co_u32_e32 v99, vcc, 0, v219, vcc
	global_load_dwordx4 v[98:101], v[98:99], off nt
	v_add_co_u32_e32 v102, vcc, s30, v218
	s_nop 1
	v_addc_co_u32_e32 v103, vcc, 0, v219, vcc
	global_load_dwordx4 v[102:105], v[102:103], off nt
	s_add_u32 s58, s58, 0x1200000
	s_addc_u32 s59, s59, 0
.Lada_loop:
	v_add_u32_e32 v37, 0x2000, v2
	v_add_u32_e32 v220, 0x4000, v2
	v_add_u32_e32 v221, 0x6000, v2
	ds_read2_b32 v[40:41], v2 offset1:32
	ds_read2_b32 v[44:45], v2 offset0:64 offset1:96
	ds_read2_b32 v[46:47], v2 offset0:128 offset1:160
	ds_read2_b32 v[106:107], v2 offset0:192 offset1:224
	ds_read2_b32 v[108:109], v37 offset1:32
	ds_read2_b32 v[110:111], v220 offset1:32
	ds_read2_b32 v[112:113], v221 offset1:32
	ds_read2_b32 v[114:115], v37 offset0:64 offset1:96
	ds_read2_b32 v[116:117], v220 offset0:64 offset1:96
	ds_read2_b32 v[118:119], v221 offset0:64 offset1:96
	ds_read2_b32 v[120:121], v37 offset0:128 offset1:160
	ds_read2_b32 v[122:123], v220 offset0:128 offset1:160
	ds_read2_b32 v[124:125], v221 offset0:128 offset1:160
	ds_read2_b32 v[126:127], v37 offset0:192 offset1:224
	ds_read2_b32 v[128:129], v220 offset0:192 offset1:224
	ds_read2_b32 v[130:131], v221 offset0:192 offset1:224
	s_waitcnt lgkmcnt(0)
	v_mov_b32_e32 v138, v109
	v_mov_b32_e32 v42, v41
	v_mov_b32_e32 v140, v111
	v_mov_b32_e32 v142, v113
	v_mov_b32_e32 v132, v45
	v_mov_b32_e32 v144, v115
	v_mov_b32_e32 v146, v117
	v_mov_b32_e32 v148, v119
	v_mov_b32_e32 v134, v47
	v_mov_b32_e32 v150, v121
	v_mov_b32_e32 v152, v123
	v_mov_b32_e32 v154, v125
	v_mov_b32_e32 v136, v107
	v_mov_b32_e32 v156, v127
	v_mov_b32_e32 v158, v129
	v_mov_b32_e32 v160, v131
	v_add_u32_e32 v2, 0x400, v2
	s_waitcnt vmcnt(7)
	v_pk_fma_f32 v[16:17], v[74:75], v[40:41], v[16:17] op_sel_hi:[1,0,1]
	v_pk_fma_f32 v[18:19], v[76:77], v[40:41], v[18:19] op_sel_hi:[1,0,1]
	v_pk_fma_f32 v[12:13], v[74:75], v[108:109], v[12:13] op_sel_hi:[1,0,1]
	v_pk_fma_f32 v[14:15], v[76:77], v[108:109], v[14:15] op_sel_hi:[1,0,1]
	v_pk_fma_f32 v[8:9], v[74:75], v[110:111], v[8:9] op_sel_hi:[1,0,1]
	v_pk_fma_f32 v[10:11], v[76:77], v[110:111], v[10:11] op_sel_hi:[1,0,1]
	v_pk_fma_f32 v[4:5], v[74:75], v[112:113], v[4:5] op_sel_hi:[1,0,1]
	v_pk_fma_f32 v[6:7], v[76:77], v[112:113], v[6:7] op_sel_hi:[1,0,1]
	s_waitcnt vmcnt(6)
	v_pk_fma_f32 v[16:17], v[78:79], v[42:43], v[16:17] op_sel_hi:[1,0,1]
	v_pk_fma_f32 v[18:19], v[80:81], v[42:43], v[18:19] op_sel_hi:[1,0,1]
	v_pk_fma_f32 v[12:13], v[78:79], v[138:139], v[12:13] op_sel_hi:[1,0,1]
	v_pk_fma_f32 v[14:15], v[80:81], v[138:139], v[14:15] op_sel_hi:[1,0,1]
	v_pk_fma_f32 v[8:9], v[78:79], v[140:141], v[8:9] op_sel_hi:[1,0,1]
	v_pk_fma_f32 v[10:11], v[80:81], v[140:141], v[10:11] op_sel_hi:[1,0,1]
	v_pk_fma_f32 v[4:5], v[78:79], v[142:143], v[4:5] op_sel_hi:[1,0,1]
	v_pk_fma_f32 v[6:7], v[80:81], v[142:143], v[6:7] op_sel_hi:[1,0,1]
	s_waitcnt vmcnt(5)
	v_pk_fma_f32 v[18:19], v[84:85], v[44:45], v[18:19] op_sel_hi:[1,0,1]
	v_pk_fma_f32 v[16:17], v[82:83], v[44:45], v[16:17] op_sel_hi:[1,0,1]
	v_pk_fma_f32 v[14:15], v[84:85], v[114:115], v[14:15] op_sel_hi:[1,0,1]
	v_pk_fma_f32 v[12:13], v[82:83], v[114:115], v[12:13] op_sel_hi:[1,0,1]
	v_pk_fma_f32 v[10:11], v[84:85], v[116:117], v[10:11] op_sel_hi:[1,0,1]
	v_pk_fma_f32 v[8:9], v[82:83], v[116:117], v[8:9] op_sel_hi:[1,0,1]
	v_pk_fma_f32 v[6:7], v[84:85], v[118:119], v[6:7] op_sel_hi:[1,0,1]
	v_pk_fma_f32 v[4:5], v[82:83], v[118:119], v[4:5] op_sel_hi:[1,0,1]
	s_waitcnt vmcnt(4)
	v_pk_fma_f32 v[18:19], v[88:89], v[132:133], v[18:19] op_sel_hi:[1,0,1]
	v_pk_fma_f32 v[16:17], v[86:87], v[132:133], v[16:17] op_sel_hi:[1,0,1]
	v_pk_fma_f32 v[14:15], v[88:89], v[144:145], v[14:15] op_sel_hi:[1,0,1]
	v_pk_fma_f32 v[12:13], v[86:87], v[144:145], v[12:13] op_sel_hi:[1,0,1]
	v_pk_fma_f32 v[10:11], v[88:89], v[146:147], v[10:11] op_sel_hi:[1,0,1]
	v_pk_fma_f32 v[8:9], v[86:87], v[146:147], v[8:9] op_sel_hi:[1,0,1]
	v_pk_fma_f32 v[6:7], v[88:89], v[148:149], v[6:7] op_sel_hi:[1,0,1]
	v_pk_fma_f32 v[4:5], v[86:87], v[148:149], v[4:5] op_sel_hi:[1,0,1]
	v_lshl_add_u64 v[218:219], v[38:39], 0, s[58:59]
	global_load_dwordx4 v[74:77], v[218:219], off nt
	v_add_co_u32_e32 v78, vcc, s2, v218
	s_nop 1
	v_addc_co_u32_e32 v79, vcc, 0, v219, vcc
	global_load_dwordx4 v[78:81], v[78:79], off nt
	v_add_co_u32_e32 v82, vcc, s9, v218
	s_nop 1
	v_addc_co_u32_e32 v83, vcc, 0, v219, vcc
	global_load_dwordx4 v[82:85], v[82:83], off nt
	v_add_co_u32_e32 v86, vcc, s19, v218
	s_nop 1
	v_addc_co_u32_e32 v87, vcc, 0, v219, vcc
	global_load_dwordx4 v[86:89], v[86:87], off nt
	s_waitcnt vmcnt(7)
; __device__ __forceinline__ void phase_prep(const Params& P, LAS unsigned char* lds, int l, const XcdBarrier& bar) {
;     ...
; #pragma unroll 8
;         for (int kk = 0; kk < 64; ++kk) { const f32x4 wv = __builtin_nontemporal_load((const f32x4*)(wp + (size_t)kk * 32 * NMOD)); const int k = kg + 32 * kk;
;             a0 += wv * sc[k]; a1 += wv * sc[DM + k]; a2 += wv * sc[2 * DM + k]; a3 += wv * sc[3 * DM + k]; }
	v_pk_fma_f32 v[18:19], v[92:93], v[46:47], v[18:19] op_sel_hi:[1,0,1]
	v_pk_fma_f32 v[16:17], v[90:91], v[46:47], v[16:17] op_sel_hi:[1,0,1]
	v_pk_fma_f32 v[14:15], v[92:93], v[120:121], v[14:15] op_sel_hi:[1,0,1]
	v_pk_fma_f32 v[12:13], v[90:91], v[120:121], v[12:13] op_sel_hi:[1,0,1]
	v_pk_fma_f32 v[10:11], v[92:93], v[122:123], v[10:11] op_sel_hi:[1,0,1]
	v_pk_fma_f32 v[8:9], v[90:91], v[122:123], v[8:9] op_sel_hi:[1,0,1]
	v_pk_fma_f32 v[6:7], v[92:93], v[124:125], v[6:7] op_sel_hi:[1,0,1]
	v_pk_fma_f32 v[4:5], v[90:91], v[124:125], v[4:5] op_sel_hi:[1,0,1]
	s_waitcnt vmcnt(6)
	v_pk_fma_f32 v[18:19], v[96:97], v[134:135], v[18:19] op_sel_hi:[1,0,1]
	v_pk_fma_f32 v[16:17], v[94:95], v[134:135], v[16:17] op_sel_hi:[1,0,1]
	v_pk_fma_f32 v[14:15], v[96:97], v[150:151], v[14:15] op_sel_hi:[1,0,1]
	v_pk_fma_f32 v[12:13], v[94:95], v[150:151], v[12:13] op_sel_hi:[1,0,1]
	v_pk_fma_f32 v[10:11], v[96:97], v[152:153], v[10:11] op_sel_hi:[1,0,1]
	v_pk_fma_f32 v[8:9], v[94:95], v[152:153], v[8:9] op_sel_hi:[1,0,1]
	v_pk_fma_f32 v[6:7], v[96:97], v[154:155], v[6:7] op_sel_hi:[1,0,1]
	v_pk_fma_f32 v[4:5], v[94:95], v[154:155], v[4:5] op_sel_hi:[1,0,1]
	s_waitcnt vmcnt(5)
	v_pk_fma_f32 v[18:19], v[100:101], v[106:107], v[18:19] op_sel_hi:[1,0,1]
	v_pk_fma_f32 v[16:17], v[98:99], v[106:107], v[16:17] op_sel_hi:[1,0,1]
	v_pk_fma_f32 v[14:15], v[100:101], v[126:127], v[14:15] op_sel_hi:[1,0,1]
	v_pk_fma_f32 v[12:13], v[98:99], v[126:127], v[12:13] op_sel_hi:[1,0,1]
	v_pk_fma_f32 v[10:11], v[100:101], v[128:129], v[10:11] op_sel_hi:[1,0,1]
	v_pk_fma_f32 v[8:9], v[98:99], v[128:129], v[8:9] op_sel_hi:[1,0,1]
	v_pk_fma_f32 v[6:7], v[100:101], v[130:131], v[6:7] op_sel_hi:[1,0,1]
	v_pk_fma_f32 v[4:5], v[98:99], v[130:131], v[4:5] op_sel_hi:[1,0,1]
	s_waitcnt vmcnt(4)
	v_pk_fma_f32 v[18:19], v[104:105], v[136:137], v[18:19] op_sel_hi:[1,0,1]
	v_pk_fma_f32 v[16:17], v[102:103], v[136:137], v[16:17] op_sel_hi:[1,0,1]
	v_pk_fma_f32 v[14:15], v[104:105], v[156:157], v[14:15] op_sel_hi:[1,0,1]
	v_pk_fma_f32 v[12:13], v[102:103], v[156:157], v[12:13] op_sel_hi:[1,0,1]
	v_pk_fma_f32 v[10:11], v[104:105], v[158:159], v[10:11] op_sel_hi:[1,0,1]
	v_pk_fma_f32 v[8:9], v[102:103], v[158:159], v[8:9] op_sel_hi:[1,0,1]
	v_pk_fma_f32 v[6:7], v[104:105], v[160:161], v[6:7] op_sel_hi:[1,0,1]
	v_pk_fma_f32 v[4:5], v[102:103], v[160:161], v[4:5] op_sel_hi:[1,0,1]
	v_add_co_u32_e32 v90, vcc, s24, v218
	s_nop 1
	v_addc_co_u32_e32 v91, vcc, 0, v219, vcc
	global_load_dwordx4 v[90:93], v[90:91], off nt
	v_add_co_u32_e32 v94, vcc, s25, v218
	s_nop 1
	v_addc_co_u32_e32 v95, vcc, 0, v219, vcc
	global_load_dwordx4 v[94:97], v[94:95], off nt
	v_add_co_u32_e32 v98, vcc, s29, v218
	s_nop 1
	v_addc_co_u32_e32 v99, vcc, 0, v219, vcc
	global_load_dwordx4 v[98:101], v[98:99], off nt
	v_add_co_u32_e32 v102, vcc, s30, v218
	s_nop 1
	v_addc_co_u32_e32 v103, vcc, 0, v219, vcc
	global_load_dwordx4 v[102:105], v[102:103], off nt
	s_add_u32 s58, s58, 0x1200000
	s_addc_u32 s59, s59, 0
	s_cmp_eq_u32 s58, 0x9000000
	s_cbranch_scc0 .Lada_loop
	v_add_u32_e32 v37, 0x2000, v2
	v_add_u32_e32 v220, 0x4000, v2
	v_add_u32_e32 v221, 0x6000, v2
	ds_read2_b32 v[40:41], v2 offset1:32
	ds_read2_b32 v[44:45], v2 offset0:64 offset1:96
	ds_read2_b32 v[46:47], v2 offset0:128 offset1:160
	ds_read2_b32 v[106:107], v2 offset0:192 offset1:224
	ds_read2_b32 v[108:109], v37 offset1:32
	ds_read2_b32 v[110:111], v220 offset1:32
	ds_read2_b32 v[112:113], v221 offset1:32
	ds_read2_b32 v[114:115], v37 offset0:64 offset1:96
	ds_read2_b32 v[116:117], v220 offset0:64 offset1:96
	ds_read2_b32 v[118:119], v221 offset0:64 offset1:96
	ds_read2_b32 v[120:121], v37 offset0:128 offset1:160
	ds_read2_b32 v[122:123], v220 offset0:128 offset1:160
	ds_read2_b32 v[124:125], v221 offset0:128 offset1:160
	ds_read2_b32 v[126:127], v37 offset0:192 offset1:224
	ds_read2_b32 v[128:129], v220 offset0:192 offset1:224
	ds_read2_b32 v[130:131], v221 offset0:192 offset1:224
	s_waitcnt lgkmcnt(0)
	v_mov_b32_e32 v138, v109
	v_mov_b32_e32 v42, v41
	v_mov_b32_e32 v140, v111
	v_mov_b32_e32 v142, v113
	v_mov_b32_e32 v132, v45
	v_mov_b32_e32 v144, v115
	v_mov_b32_e32 v146, v117
	v_mov_b32_e32 v148, v119
	v_mov_b32_e32 v134, v47
	v_mov_b32_e32 v150, v121
	v_mov_b32_e32 v152, v123
	v_mov_b32_e32 v154, v125
	v_mov_b32_e32 v136, v107
	v_mov_b32_e32 v156, v127
	v_mov_b32_e32 v158, v129
	v_mov_b32_e32 v160, v131
	v_add_u32_e32 v2, 0x400, v2
	s_waitcnt vmcnt(7)
	v_pk_fma_f32 v[16:17], v[74:75], v[40:41], v[16:17] op_sel_hi:[1,0,1]
	v_pk_fma_f32 v[18:19], v[76:77], v[40:41], v[18:19] op_sel_hi:[1,0,1]
	v_pk_fma_f32 v[12:13], v[74:75], v[108:109], v[12:13] op_sel_hi:[1,0,1]
	v_pk_fma_f32 v[14:15], v[76:77], v[108:109], v[14:15] op_sel_hi:[1,0,1]
	v_pk_fma_f32 v[8:9], v[74:75], v[110:111], v[8:9] op_sel_hi:[1,0,1]
	v_pk_fma_f32 v[10:11], v[76:77], v[110:111], v[10:11] op_sel_hi:[1,0,1]
	v_pk_fma_f32 v[4:5], v[74:75], v[112:113], v[4:5] op_sel_hi:[1,0,1]
	v_pk_fma_f32 v[6:7], v[76:77], v[112:113], v[6:7] op_sel_hi:[1,0,1]
	s_waitcnt vmcnt(6)
	v_pk_fma_f32 v[16:17], v[78:79], v[42:43], v[16:17] op_sel_hi:[1,0,1]
	v_pk_fma_f32 v[18:19], v[80:81], v[42:43], v[18:19] op_sel_hi:[1,0,1]
	v_pk_fma_f32 v[12:13], v[78:79], v[138:139], v[12:13] op_sel_hi:[1,0,1]
	v_pk_fma_f32 v[14:15], v[80:81], v[138:139], v[14:15] op_sel_hi:[1,0,1]
	v_pk_fma_f32 v[8:9], v[78:79], v[140:141], v[8:9] op_sel_hi:[1,0,1]
	v_pk_fma_f32 v[10:11], v[80:81], v[140:141], v[10:11] op_sel_hi:[1,0,1]
	v_pk_fma_f32 v[4:5], v[78:79], v[142:143], v[4:5] op_sel_hi:[1,0,1]
	v_pk_fma_f32 v[6:7], v[80:81], v[142:143], v[6:7] op_sel_hi:[1,0,1]
	s_waitcnt vmcnt(5)
; __device__ __forceinline__ void phase_prep(const Params& P, LAS unsigned char* lds, int l, const XcdBarrier& bar) {
;     ...
; #pragma unroll 8
;         for (int kk = 0; kk < 64; ++kk) { const f32x4 wv = __builtin_nontemporal_load((const f32x4*)(wp + (size_t)kk * 32 * NMOD)); const int k = kg + 32 * kk;
;             a0 += wv * sc[k]; a1 += wv * sc[DM + k]; a2 += wv * sc[2 * DM + k]; a3 += wv * sc[3 * DM + k]; }
; #pragma unroll
;         for (int e = 0; e < 4; ++e) { red[kg * 256 + 0 * 64 + 4 * cq + e] = a0[e]; red[kg * 256 + 1 * 64 + 4 * cq + e] = a1[e]; red[kg * 256 + 2 * 64 + 4 * cq + e] = a2[e]; red[kg * 256 + 3 * 64 + 4 * cq + e] = a3[e]; }
;         __syncthreads();
;         if (tid < 256) { float s = 0.f;
; #pragma unroll
;             for (int q = 0; q < 32; ++q) s += red[q * 256 + tid];
;             const int b = tid >> 6, col = col0 + (tid & 63);
;             mod[(size_t)(ll * NBATCH + b) * NMOD + col] = s + P.ada_b[(size_t)ll * NMOD + col]; }
	v_pk_fma_f32 v[18:19], v[84:85], v[44:45], v[18:19] op_sel_hi:[1,0,1]
	v_pk_fma_f32 v[16:17], v[82:83], v[44:45], v[16:17] op_sel_hi:[1,0,1]
	v_pk_fma_f32 v[14:15], v[84:85], v[114:115], v[14:15] op_sel_hi:[1,0,1]
	v_pk_fma_f32 v[12:13], v[82:83], v[114:115], v[12:13] op_sel_hi:[1,0,1]
	v_pk_fma_f32 v[10:11], v[84:85], v[116:117], v[10:11] op_sel_hi:[1,0,1]
	v_pk_fma_f32 v[8:9], v[82:83], v[116:117], v[8:9] op_sel_hi:[1,0,1]
	v_pk_fma_f32 v[6:7], v[84:85], v[118:119], v[6:7] op_sel_hi:[1,0,1]
	v_pk_fma_f32 v[4:5], v[82:83], v[118:119], v[4:5] op_sel_hi:[1,0,1]
	s_waitcnt vmcnt(4)
	v_pk_fma_f32 v[18:19], v[88:89], v[132:133], v[18:19] op_sel_hi:[1,0,1]
	v_pk_fma_f32 v[16:17], v[86:87], v[132:133], v[16:17] op_sel_hi:[1,0,1]
	v_pk_fma_f32 v[14:15], v[88:89], v[144:145], v[14:15] op_sel_hi:[1,0,1]
	v_pk_fma_f32 v[12:13], v[86:87], v[144:145], v[12:13] op_sel_hi:[1,0,1]
	v_pk_fma_f32 v[10:11], v[88:89], v[146:147], v[10:11] op_sel_hi:[1,0,1]
	v_pk_fma_f32 v[8:9], v[86:87], v[146:147], v[8:9] op_sel_hi:[1,0,1]
	v_pk_fma_f32 v[6:7], v[88:89], v[148:149], v[6:7] op_sel_hi:[1,0,1]
	v_pk_fma_f32 v[4:5], v[86:87], v[148:149], v[4:5] op_sel_hi:[1,0,1]
	s_waitcnt vmcnt(3)
	v_pk_fma_f32 v[18:19], v[92:93], v[46:47], v[18:19] op_sel_hi:[1,0,1]
	v_pk_fma_f32 v[16:17], v[90:91], v[46:47], v[16:17] op_sel_hi:[1,0,1]
	v_pk_fma_f32 v[14:15], v[92:93], v[120:121], v[14:15] op_sel_hi:[1,0,1]
	v_pk_fma_f32 v[12:13], v[90:91], v[120:121], v[12:13] op_sel_hi:[1,0,1]
	v_pk_fma_f32 v[10:11], v[92:93], v[122:123], v[10:11] op_sel_hi:[1,0,1]
	v_pk_fma_f32 v[8:9], v[90:91], v[122:123], v[8:9] op_sel_hi:[1,0,1]
	v_pk_fma_f32 v[6:7], v[92:93], v[124:125], v[6:7] op_sel_hi:[1,0,1]
	v_pk_fma_f32 v[4:5], v[90:91], v[124:125], v[4:5] op_sel_hi:[1,0,1]
	s_waitcnt vmcnt(2)
	v_pk_fma_f32 v[18:19], v[96:97], v[134:135], v[18:19] op_sel_hi:[1,0,1]
	v_pk_fma_f32 v[16:17], v[94:95], v[134:135], v[16:17] op_sel_hi:[1,0,1]
	v_pk_fma_f32 v[14:15], v[96:97], v[150:151], v[14:15] op_sel_hi:[1,0,1]
	v_pk_fma_f32 v[12:13], v[94:95], v[150:151], v[12:13] op_sel_hi:[1,0,1]
	v_pk_fma_f32 v[10:11], v[96:97], v[152:153], v[10:11] op_sel_hi:[1,0,1]
	v_pk_fma_f32 v[8:9], v[94:95], v[152:153], v[8:9] op_sel_hi:[1,0,1]
	v_pk_fma_f32 v[6:7], v[96:97], v[154:155], v[6:7] op_sel_hi:[1,0,1]
	v_pk_fma_f32 v[4:5], v[94:95], v[154:155], v[4:5] op_sel_hi:[1,0,1]
	s_waitcnt vmcnt(1)
	v_pk_fma_f32 v[18:19], v[100:101], v[106:107], v[18:19] op_sel_hi:[1,0,1]
	v_pk_fma_f32 v[16:17], v[98:99], v[106:107], v[16:17] op_sel_hi:[1,0,1]
	v_pk_fma_f32 v[14:15], v[100:101], v[126:127], v[14:15] op_sel_hi:[1,0,1]
	v_pk_fma_f32 v[12:13], v[98:99], v[126:127], v[12:13] op_sel_hi:[1,0,1]
	v_pk_fma_f32 v[10:11], v[100:101], v[128:129], v[10:11] op_sel_hi:[1,0,1]
	v_pk_fma_f32 v[8:9], v[98:99], v[128:129], v[8:9] op_sel_hi:[1,0,1]
	v_pk_fma_f32 v[6:7], v[100:101], v[130:131], v[6:7] op_sel_hi:[1,0,1]
	v_pk_fma_f32 v[4:5], v[98:99], v[130:131], v[4:5] op_sel_hi:[1,0,1]
	s_waitcnt vmcnt(0)
	v_pk_fma_f32 v[18:19], v[104:105], v[136:137], v[18:19] op_sel_hi:[1,0,1]
	v_pk_fma_f32 v[16:17], v[102:103], v[136:137], v[16:17] op_sel_hi:[1,0,1]
	v_pk_fma_f32 v[14:15], v[104:105], v[156:157], v[14:15] op_sel_hi:[1,0,1]
	v_pk_fma_f32 v[12:13], v[102:103], v[156:157], v[12:13] op_sel_hi:[1,0,1]
	v_pk_fma_f32 v[10:11], v[104:105], v[158:159], v[10:11] op_sel_hi:[1,0,1]
	v_pk_fma_f32 v[8:9], v[102:103], v[158:159], v[8:9] op_sel_hi:[1,0,1]
	v_pk_fma_f32 v[6:7], v[104:105], v[160:161], v[6:7] op_sel_hi:[1,0,1]
	v_pk_fma_f32 v[4:5], v[102:103], v[160:161], v[4:5] op_sel_hi:[1,0,1]
	v_readlane_b32 s18, v247, 23
	v_readlane_b32 s19, v247, 24
	ds_write_b128 v69, v[16:19] offset:32768
	ds_write_b128 v69, v[12:15] offset:33024
	ds_write_b128 v69, v[8:11] offset:33280
	ds_write_b128 v69, v[4:7] offset:33536
	s_waitcnt lgkmcnt(0)
	s_barrier
	s_and_saveexec_b64 s[58:59], s[18:19]
	s_cbranch_execz .LBB0_270
	v_readlane_b32 s60, v250, 39
	v_or_b32_e32 v4, s54, v48
	s_mul_i32 s19, s8, 0x12000
	v_readlane_b32 s66, v250, 45
	v_ashrrev_i32_e32 v5, 31, v4
	s_mul_hi_i32 s9, s8, 0x12000
	v_readlane_b32 s67, v250, 46
	s_add_u32 s24, s66, s19
	s_addc_u32 s25, s67, s9
	v_lshlrev_b64 v[4:5], 2, v[4:5]
	v_lshl_add_u64 v[6:7], s[24:25], 0, v[4:5]
	global_load_dword v2, v[6:7], off
	ds_read2st64_b32 v[6:7], v70 offset0:128 offset1:132
	ds_read2st64_b32 v[8:9], v70 offset0:136 offset1:140
	ds_read2st64_b32 v[10:11], v70 offset0:144 offset1:148
	ds_read2st64_b32 v[12:13], v70 offset0:152 offset1:156
	ds_read2st64_b32 v[14:15], v70 offset0:160 offset1:164
	ds_read2st64_b32 v[16:17], v70 offset0:168 offset1:172
	ds_read2st64_b32 v[18:19], v70 offset0:176 offset1:180
	ds_read2st64_b32 v[38:39], v70 offset0:184 offset1:188
	ds_read2st64_b32 v[40:41], v70 offset0:192 offset1:196
	ds_read2st64_b32 v[42:43], v70 offset0:200 offset1:204
	ds_read2st64_b32 v[44:45], v70 offset0:208 offset1:212
	ds_read2st64_b32 v[46:47], v70 offset0:216 offset1:220
	ds_read2st64_b32 v[74:75], v70 offset0:224 offset1:228
	ds_read2st64_b32 v[76:77], v70 offset0:232 offset1:236
	ds_read2st64_b32 v[78:79], v70 offset0:240 offset1:244
	ds_read2st64_b32 v[80:81], v70 offset0:248 offset1:252
	s_waitcnt lgkmcnt(14)
	v_add_f32_e32 v6, 0, v6
	v_add_f32_e32 v6, v6, v7
	v_add_f32_e32 v6, v6, v8
	v_add_f32_e32 v6, v6, v9
	s_waitcnt lgkmcnt(13)
	v_add_f32_e32 v6, v6, v10
	v_add_f32_e32 v6, v6, v11
	s_waitcnt lgkmcnt(12)
	v_add_f32_e32 v6, v6, v12
	v_add_f32_e32 v6, v6, v13
	s_waitcnt lgkmcnt(11)
	v_add_f32_e32 v6, v6, v14
	v_add_f32_e32 v6, v6, v15
	s_waitcnt lgkmcnt(10)
	v_add_f32_e32 v6, v6, v16
	v_add_f32_e32 v6, v6, v17
	s_waitcnt lgkmcnt(9)
	v_add_f32_e32 v6, v6, v18
	v_add_f32_e32 v6, v6, v19
	s_waitcnt lgkmcnt(8)
	v_add_f32_e32 v6, v6, v38
	v_add_f32_e32 v6, v6, v39
	s_waitcnt lgkmcnt(7)
	v_add_f32_e32 v6, v6, v40
	v_add_f32_e32 v6, v6, v41
	s_waitcnt lgkmcnt(6)
	v_add_f32_e32 v6, v6, v42
	v_add_f32_e32 v6, v6, v43
	s_waitcnt lgkmcnt(5)
	v_add_f32_e32 v6, v6, v44
	v_add_f32_e32 v6, v6, v45
	s_waitcnt lgkmcnt(4)
	v_add_f32_e32 v6, v6, v46
	v_add_f32_e32 v6, v6, v47
	s_waitcnt lgkmcnt(3)
	v_add_f32_e32 v6, v6, v74
	v_add_f32_e32 v6, v6, v75
	s_waitcnt lgkmcnt(2)
	v_add_f32_e32 v6, v6, v76
	v_add_f32_e32 v6, v6, v77
	s_waitcnt lgkmcnt(1)
	v_add_f32_e32 v6, v6, v78
	v_add_f32_e32 v6, v6, v79
	v_lshl_add_u32 v37, s8, 2, v27
	v_mov_b64_e32 v[82:83], s[4:5]
	s_waitcnt lgkmcnt(0)
	v_add_f32_e32 v6, v6, v80
	v_mad_i64_i32 v[82:83], s[8:9], v37, s6, v[82:83]
	v_add_f32_e32 v6, v6, v81
	v_lshl_add_u64 v[4:5], v[82:83], 0, v[4:5]
	v_readlane_b32 s61, v250, 40
	v_readlane_b32 s62, v250, 41
	v_readlane_b32 s63, v250, 42
	v_readlane_b32 s64, v250, 43
	v_readlane_b32 s65, v250, 44
	v_readlane_b32 s68, v250, 47
	v_readlane_b32 s69, v250, 48
	v_readlane_b32 s70, v250, 49
	v_readlane_b32 s71, v250, 50
	v_readlane_b32 s72, v250, 51
	v_readlane_b32 s73, v250, 52
	v_readlane_b32 s74, v250, 53
	v_readlane_b32 s75, v250, 54
	s_waitcnt vmcnt(0)
	v_add_f32_e32 v2, v6, v2
	global_store_dword v[4:5], v2, off
	s_branch .LBB0_270
